# P2b queue order: query blocks 15..6 as before, remaining units sorted longest-first (diff qb5..2, memory units, then the small sb/diff units); on top of v58
# speedup vs baseline: 1.0123x; 1.0066x over previous
.LBB0_349:
	v_readlane_b32 s0, v255, 16
	s_waitcnt lgkmcnt(0)
	s_barrier
	v_mov_b32_e32 v0, s0
	ds_read_b32 v0, v0
	s_movk_i32 s0, 0x4ff
	s_waitcnt lgkmcnt(0)
	s_barrier
	v_cmp_lt_u32_e32 vcc, s0, v0
	v_readfirstlane_b32 s16, v0
	s_mov_b64 s[0:1], -1
	s_cbranch_vccnz .LBB0_342
	s_lshr_b32 s4, s16, 5
	s_lshr_b32 s5, s4, 2
	s_and_b32 s4, s4, 3
	s_lshl_b32 s4, s4, 3
	s_mov_b32 vcc_lo, 0x3020100
	s_cmp_eq_u32 s5, 1
	s_cselect_b32 vcc_lo, 0x7060504, vcc_lo
	s_cmp_eq_u32 s5, 2
	s_cselect_b32 vcc_lo, 0xb0a0908, vcc_lo
	s_cmp_eq_u32 s5, 3
	s_cselect_b32 vcc_lo, 0xf0e0d0c, vcc_lo
	s_cmp_eq_u32 s5, 4
	s_cselect_b32 vcc_lo, 0x13121110, vcc_lo
	s_cmp_eq_u32 s5, 5
	s_cselect_b32 vcc_lo, 0x1b191715, vcc_lo
	s_cmp_eq_u32 s5, 6
	s_cselect_b32 vcc_lo, 0x23222120, vcc_lo
	s_cmp_eq_u32 s5, 7
	s_cselect_b32 vcc_lo, 0x27262524, vcc_lo
	s_cmp_eq_u32 s5, 8
	s_cselect_b32 vcc_lo, 0x18161d14, vcc_lo
	s_cmp_eq_u32 s5, 9
	s_cselect_b32 vcc_lo, 0x1e1c1a1f, vcc_lo
	s_lshr_b32 vcc_lo, vcc_lo, s4
	s_and_b32 vcc_lo, vcc_lo, 0xff
	s_lshl_b32 vcc_lo, vcc_lo, 5
	s_and_b32 s16, s16, 31
	s_or_b32 s16, s16, vcc_lo
	s_cmpk_gt_u32 s16, 0x3ff
	s_cbranch_scc0 .LBB0_352
	v_readlane_b32 s0, v255, 55
	v_readlane_b32 s1, v255, 56
	v_readlane_b32 s4, v255, 22
	s_add_i32 s4, s4, 2
	s_mul_i32 s4, s4, s80
	v_mov_b32_e32 v0, 0
	s_mov_b32 s5, 0
	s_nop 3
